# chain workgroups go straight to the phase seam after their chain in the 256-workgroup geometry (the pool workgroups drain all queues)
# speedup vs baseline: 1.0037x; 1.0037x over previous
.LBB0_1096:
	s_or_b64 exec, exec, s[6:7]
	v_pk_mul_f32 v[2:3], v[20:21], v[10:11]
	s_waitcnt vmcnt(2)
	v_lshlrev_b32_e32 v10, 16, v36
	v_and_b32_e32 v11, 0xffff0000, v36
	v_mul_f32_e32 v12, 0xbfb8aa3b, v10
	v_mul_f32_e32 v13, 0xbfb8aa3b, v11
	v_exp_f32_e32 v12, v12
	v_exp_f32_e32 v13, v13
	v_add_co_u32_e32 v0, vcc, 0x12840000, v0
	v_add_f32_e32 v12, 1.0, v12
	v_add_f32_e32 v13, 1.0, v13
	v_rcp_f32_e32 v12, v12
	v_rcp_f32_e32 v13, v13
	v_addc_co_u32_e32 v1, vcc, 0, v1, vcc
	v_pk_mul_f32 v[10:11], v[12:13], v[10:11]
	s_nop 0
	v_pk_mul_f32 v[2:3], v[10:11], v[2:3]
	s_nop 0
	v_cvt_pk_bf16_f32 v10, v2, v3
	v_pk_mul_f32 v[2:3], v[22:23], v[8:9]
	v_lshlrev_b32_e32 v8, 16, v37
	v_mul_f32_e32 v11, 0xbfb8aa3b, v8
	v_exp_f32_e32 v11, v11
	v_and_b32_e32 v9, 0xffff0000, v37
	v_add_f32_e32 v11, 1.0, v11
	v_rcp_f32_e32 v12, v11
	v_mul_f32_e32 v11, 0xbfb8aa3b, v9
	v_exp_f32_e32 v11, v11
	s_nop 0
	v_add_f32_e32 v11, 1.0, v11
	v_rcp_f32_e32 v13, v11
	s_nop 0
	v_pk_mul_f32 v[8:9], v[12:13], v[8:9]
	s_nop 0
	v_pk_mul_f32 v[2:3], v[8:9], v[2:3]
	s_nop 0
	v_cvt_pk_bf16_f32 v11, v2, v3
	v_pk_mul_f32 v[2:3], v[16:17], v[6:7]
	v_lshlrev_b32_e32 v6, 16, v38
	v_and_b32_e32 v7, 0xffff0000, v38
	v_mul_f32_e32 v8, 0xbfb8aa3b, v6
	v_mul_f32_e32 v9, 0xbfb8aa3b, v7
	v_exp_f32_e32 v8, v8
	v_exp_f32_e32 v9, v9
	v_add_f32_e32 v8, 1.0, v8
	v_add_f32_e32 v9, 1.0, v9
	v_rcp_f32_e32 v8, v8
	v_rcp_f32_e32 v9, v9
	s_nop 0
	v_pk_mul_f32 v[6:7], v[8:9], v[6:7]
	s_nop 0
	v_pk_mul_f32 v[2:3], v[6:7], v[2:3]
	s_nop 0
	v_cvt_pk_bf16_f32 v12, v2, v3
	v_pk_mul_f32 v[2:3], v[18:19], v[4:5]
	v_lshlrev_b32_e32 v4, 16, v39
	v_and_b32_e32 v5, 0xffff0000, v39
	v_mul_f32_e32 v6, 0xbfb8aa3b, v4
	v_mul_f32_e32 v7, 0xbfb8aa3b, v5
	v_exp_f32_e32 v6, v6
	v_exp_f32_e32 v7, v7
	v_add_f32_e32 v6, 1.0, v6
	v_add_f32_e32 v7, 1.0, v7
	v_rcp_f32_e32 v6, v6
	v_rcp_f32_e32 v7, v7
	s_nop 0
	v_pk_mul_f32 v[4:5], v[6:7], v[4:5]
	s_nop 0
	v_pk_mul_f32 v[2:3], v[4:5], v[2:3]
	s_nop 0
	v_cvt_pk_bf16_f32 v13, v2, v3
	global_store_dwordx4 v[0:1], v[10:13], off
	s_waitcnt lgkmcnt(0)
	s_barrier
	s_barrier
	s_load_dword s4, s[0:1], 0x70
	s_waitcnt lgkmcnt(0)
	s_cmpk_eq_i32 s4, 0x100
	s_cbranch_scc1 .LBB0_1126
	s_mov_b32 s31, -1
	s_branch .LBB0_1098
